# v31 plus weight conversion in three pieces per target layer: 1 item per wave in the w_in phase, 2 per wave at the gate_up phase start (CUs 128-255), remainder at the next w_in phase start (CUs 224-247
# speedup vs baseline: 1.0333x; 1.0037x over previous
; __device__ __forceinline__ ArgsP args_ptr() { ArgsP p = (ArgsP)__builtin_amdgcn_kernarg_segment_ptr(); asm volatile("" : "+s"(p)); return p; }
; __device__ __forceinline__ void convert_layer(ArgsP a, int L, int first, int stride, int lane) {
;     ...
;     for (int r = first; r < I_L; r += stride) {
;         if (r < I_IN) transpose_item(a->in[3] + (size_t)L * D * INW, D, INW, WIN + (size_t)L * INW * D, a->in[2] + L * D, 1, 0, r, lane);
;         else if (r < I_IN + I_OUT) transpose_item(a->in[4] + (size_t)L * D * D, D, D, WOUT + (size_t)L * D * D, nullptr, 0, 0, r - I_IN, lane);
;         else if (r < I_IN + I_OUT + I_GU) transpose_item(a->in[18] + (size_t)L * D * GU, D, GU, WGU + (size_t)L * GU * D, a->in[17] + L * D, 2, 0, r - I_IN - I_OUT, lane);
;         else transpose_item(a->in[19] + (size_t)L * FFN * D, FFN, D, WDN + (size_t)L * D * FFN, nullptr, 0, 0, r - I_IN - I_OUT - I_GU, lane);
;     }
; __device__ __forceinline__ void phase_A(unsigned char* lds, int wave_s, int L) {
;     ...
;     if (L + 1 < DEPTH && bx >= 128 && bx < 224) { convert_layer(args_ptr(), L + 1, (bx - 128) * NWAVES + wave, 96 * NWAVES, lane); asm volatile("s_waitcnt vmcnt(0)" ::: "memory"); }
.LBB0_88:
	s_add_i32 s4, s1, 0x300
	s_addk_i32 s26, 0x6000
	s_addk_i32 s27, 0xc00
	s_add_i32 s3, s3, 0xc000
	v_add_u32_e32 v82, 0xc000, v82
	s_cmpk_lt_i32 s1, 0
	s_mov_b32 s1, s4
	global_store_dwordx4 v[78:79], v[0:3], off offset:112
	s_cbranch_scc0 .LBB0_108

; __device__ __forceinline__ ArgsP args_ptr() { ArgsP p = (ArgsP)__builtin_amdgcn_kernarg_segment_ptr(); asm volatile("" : "+s"(p)); return p; }
; #define TIDS() int lane_ = (int)__builtin_amdgcn_mbcnt_hi(~0u, __builtin_amdgcn_mbcnt_lo(~0u, 0u)); asm volatile("" : "+v"(lane_)); const int lane = lane_ & 63, wave = wave_s & 7, tid = wave * 64 + lane; const int G = gridDim.x, bx = blockIdx.x; (void)lane; (void)wave; (void)tid; (void)G; (void)bx
; __device__ __forceinline__ void convert_layer(ArgsP a, int L, int first, int stride, int lane) {
;     unsigned char* ws = a->ws;
;     bf16* WIN = (bf16*)(ws + WS_WIN); bf16* WOUT = (bf16*)(ws + WS_WOUT); bf16* WGU = (bf16*)(ws + WS_WGU); bf16* WDN = (bf16*)(ws + WS_WDN);
;     for (int r = first; r < I_L; r += stride) {
;         if (r < I_IN) transpose_item(a->in[3] + (size_t)L * D * INW, D, INW, WIN + (size_t)L * INW * D, a->in[2] + L * D, 1, 0, r, lane);
;         else if (r < I_IN + I_OUT) transpose_item(a->in[4] + (size_t)L * D * D, D, D, WOUT + (size_t)L * D * D, nullptr, 0, 0, r - I_IN, lane);
;         else if (r < I_IN + I_OUT + I_GU) transpose_item(a->in[18] + (size_t)L * D * GU, D, GU, WGU + (size_t)L * GU * D, a->in[17] + L * D, 2, 0, r - I_IN - I_OUT, lane);
;         else transpose_item(a->in[19] + (size_t)L * FFN * D, FFN, D, WDN + (size_t)L * D * FFN, nullptr, 0, 0, r - I_IN - I_OUT - I_GU, lane);
;     }
; }
; __device__ __forceinline__ void phase_D(unsigned char* lds, int wave_s, int L) {
;     ArgsP a = args_ptr(); TIDS(); unsigned char* ws = a->ws;
;     pg8::Gemm g{(bf16*)(ws + WS_XB), (bf16*)(ws + WS_WGU) + (size_t)L * GU * D, M, GU, D}; pg8::StaticOrder S; S.init(M, GU, G, bx);
;     pg8::EpiSwi E{(bf16*)(ws + WS_ACT), (const float*)(ws + WS_SS)};
;     pg8::gemm_phase<pg8::EpiSwi, pg8::StaticOrder, true, true>((pg8::PG8_LAS_T*)lds, g, S, E, tid);
.LBB0_511:
	s_or_b64 exec, exec, s[10:11]
	s_mov_b64 s[10:11], s[96:97]
	s_waitcnt lgkmcnt(0)
	v_mov_b32_e32 v0, v201
	v_readlane_b32 s1, v252, 5
	s_barrier
	s_cmp_lt_u32 s2, 0x80
	s_cbranch_scc1 .Lcx1_skip
	s_cmp_ge_u32 s2, 0x100
	s_cbranch_scc1 .Lcx1_skip
	v_mov_b32_e32 v128, v0
	v_mov_b32_e32 v129, v2
	v_mov_b32_e32 v130, v3
	v_mov_b32_e32 v131, v64
	v_mov_b32_e32 v132, v65
	v_mov_b32_e32 v133, v66
	v_mov_b32_e32 v134, v67
	v_mov_b32_e32 v135, v68
	v_mov_b32_e32 v136, v69
	v_mov_b32_e32 v137, v70
	v_mov_b32_e32 v138, v71
	v_mov_b32_e32 v139, v72
	v_mov_b32_e32 v140, v73
	v_mov_b32_e32 v141, v74
	v_mov_b32_e32 v142, v75
	v_mov_b32_e32 v143, v76
	v_mov_b32_e32 v144, v77
	v_mov_b32_e32 v145, v78
	v_mov_b32_e32 v146, v79
	v_mov_b32_e32 v147, v81
	v_mov_b32_e32 v148, v82
	v_mov_b32_e32 v149, v83
	v_mov_b32_e32 v150, v84
	v_mov_b32_e32 v151, v85
	v_mov_b32_e32 v152, v86
	v_mov_b32_e32 v153, v87
	v_mov_b32_e32 v154, v88
	v_mov_b32_e32 v155, v89
	v_mov_b32_e32 v156, v90
	v_mov_b32_e32 v157, v91
	v_writelane_b32 v253, s1, 0
	v_writelane_b32 v253, s6, 1
	v_writelane_b32 v253, s7, 2
	v_writelane_b32 v253, s16, 3
	v_writelane_b32 v253, s34, 4
	v_writelane_b32 v253, s35, 5
	v_writelane_b32 v253, s36, 6
	v_writelane_b32 v253, s38, 7
	v_writelane_b32 v253, s39, 8
	v_writelane_b32 v253, s44, 9
	v_writelane_b32 v253, s46, 10
	v_writelane_b32 v253, s59, 11
	v_writelane_b32 v253, s60, 12
	v_writelane_b32 v253, s61, 13
	v_writelane_b32 v253, s70, 14
	v_writelane_b32 v253, s71, 15
	v_writelane_b32 v253, s72, 16
	v_writelane_b32 v253, s86, 17
	v_writelane_b32 v253, s87, 18
	v_and_b32_e32 v80, 63, v201
	s_mov_b64 s[12:13], s[96:97]
	s_load_dwordx2 s[4:5], s[12:13], 0xa8
	v_readlane_b32 s1, v252, 2
	v_readlane_b32 s14, v252, 1
	s_nop 3
	s_add_i32 s1, s1, s14
	s_add_i32 s1, s1, 0xffffff00
	v_lshlrev_b32_e32 v0, 2, v80
	s_waitcnt lgkmcnt(0)
	s_add_u32 s14, s4, 0x4e80000
	s_addc_u32 s15, s5, 0
	s_add_u32 s16, s4, 0x2800000
	s_addc_u32 s17, s5, 0
	s_add_u32 s18, s4, 0x1700000
	s_addc_u32 s19, s5, 0
	s_add_u32 s22, s4, 0x600000
	s_addc_u32 s23, s5, 0
	s_lshl_b32 s3, s1, 6
	v_and_b32_e32 v81, 0x80, v0
	v_or_b32_e32 v82, s3, v80
	s_lshl_b32 s26, s1, 5
	s_lshl_b32 s27, s1, 2
	v_mov_b32_e32 v13, 0
	s_movk_i32 s30, 0x7fff
	s_mov_b32 s31, 0xffff0000
	v_mov_b32_e32 v83, 0x1000
	v_mov_b32_e32 v84, 1
	s_mov_b32 s33, 0xa0f000
	s_mov_b32 s34, 0xa11000
	s_mov_b32 s35, 0xa14000
	s_mov_b32 s36, 0xa16000
	s_mov_b32 s37, 0xa19000
	s_mov_b32 s38, 0xa1b000
	s_mov_b32 s39, 0xa1e000
	s_mov_b32 s40, 0xa20000
	s_mov_b32 s41, 0xa23000
	s_mov_b32 s42, 0xa25000
	s_mov_b32 s43, 0xa28000
	s_mov_b32 s44, 0xa2a000
	s_mov_b32 s45, 0xa2d000
	s_mov_b32 s46, 0xa2f000
	s_mov_b32 s47, 0xa32000
	s_mov_b32 s48, 0xa34000
	s_mov_b32 s49, 0xa37000
	s_mov_b32 s50, 0xa39000
	s_mov_b32 s51, 0xa3c000
	s_mov_b32 s52, 0xa3e000
	s_mov_b32 s53, 0xa41000
	s_mov_b32 s54, 0xa43000
	s_mov_b32 s55, 0xa46000
	s_mov_b32 s56, 0xa48000
	s_mov_b32 s57, 0xa4b000
	s_mov_b32 s58, 0xa4d000
	s_mov_b32 s59, 0xa50000
	s_mov_b32 s60, 0xa52000
	s_mov_b32 s61, 0xa55000
	s_mov_b32 s62, 0xa57000
	s_mov_b32 s63, 0xa5a000
	s_mov_b32 s64, 0xa5c000
	s_mov_b32 s65, 0xa5f000
	s_mov_b32 s66, 0xa61000
	s_mov_b32 s67, 0xa64000
	s_mov_b32 s68, 0xa66000
	s_mov_b32 s69, 0xa69000
	s_mov_b32 s70, 0xa6b000
	s_mov_b32 s71, 0xa6e000
	s_mov_b32 s72, 0xa70000
	s_mov_b32 s73, 0xa73000
	s_mov_b32 s74, 0xa75000
	s_mov_b32 s75, 0xa78000
	s_mov_b32 s76, 0xa7a000
	s_mov_b32 s77, 0xa7d000
	s_mov_b32 s78, 0xa7f000
	s_mov_b32 s79, 0xa82000
	s_mov_b32 s80, 0xa84000
	s_mov_b32 s81, 0xa87000
	s_mov_b32 s82, 0xa89000
	s_mov_b32 s83, 0xa8c000
	s_mov_b32 s84, 0xa8e000
	s_mov_b32 s85, 0xa91000
	s_mov_b32 s86, 0xa93000
	s_mov_b32 s87, 0xa96000
	s_mov_b32 s88, 0xa98000
	s_mov_b32 s89, 0xa9b000
	s_mov_b32 s90, 0xa9d000
	s_mov_b32 s25, 0
	s_branch .Lcx1_89

; __device__ __forceinline__ unsigned pk2(float lo, float hi) { return f2bf(lo) | (f2bf(hi) << 16); }
; __device__ __forceinline__ void transpose_item(const float* __restrict__ W, int K, int N, bf16* __restrict__ WT, const float* __restrict__ ksc, int mode, int row_off, int item, int lane) {
;     const int nblk = N / 64, kb = item / nblk, nb = item % nblk, k0 = 64 * kb, n = 64 * nb + lane;
;     const float* src = W + (size_t)k0 * N + n;
;     float v[64];
; #pragma unroll
;     for (int i = 0; i < 64; ++i) v[i] = __builtin_nontemporal_load(src + (size_t)i * N);
;     if (ksc) {
; #pragma unroll
;         for (int i = 0; i < 64; ++i) v[i] *= ksc[k0 + i];
;     }
;     bf16* dst = WT + (size_t)(row_off + map_row(n, mode)) * K + k0;
; #pragma unroll
;     for (int j = 0; j < 8; ++j) { v4u o; o.x = pk2(v[8 * j], v[8 * j + 1]); o.y = pk2(v[8 * j + 2], v[8 * j + 3]); o.z = pk2(v[8 * j + 4], v[8 * j + 5]); o.w = pk2(v[8 * j + 6], v[8 * j + 7]);
;         *(v4u*)(dst + 8 * j) = o; }
; __device__ __forceinline__ void convert_layer(ArgsP a, int L, int first, int stride, int lane) {
;     ...
;     for (int r = first; r < I_L; r += stride) {
;         if (r < I_IN) transpose_item(a->in[3] + (size_t)L * D * INW, D, INW, WIN + (size_t)L * INW * D, a->in[2] + L * D, 1, 0, r, lane);
;         else if (r < I_IN + I_OUT) transpose_item(a->in[4] + (size_t)L * D * D, D, D, WOUT + (size_t)L * D * D, nullptr, 0, 0, r - I_IN, lane);
;         else if (r < I_IN + I_OUT + I_GU) transpose_item(a->in[18] + (size_t)L * D * GU, D, GU, WGU + (size_t)L * GU * D, a->in[17] + L * D, 2, 0, r - I_IN - I_OUT, lane);
;         else transpose_item(a->in[19] + (size_t)L * FFN * D, FFN, D, WDN + (size_t)L * D * FFN, nullptr, 0, 0, r - I_IN - I_OUT - I_GU, lane);
;     }
.Lcx1_88:
	s_add_i32 s4, s1, 0x400
	s_add_i32 s26, s26, 0x8000
	s_add_i32 s27, s27, 0x1000
	s_add_i32 s3, s3, 0x10000
	v_add_u32_e32 v82, 0x10000, v82
	s_cmpk_lt_i32 s1, 0x700
	s_mov_b32 s1, s4
	global_store_dwordx4 v[78:79], v[0:3], off offset:112
	s_cbranch_scc0 .Lcx1_108

; __device__ __forceinline__ ArgsP args_ptr() { ArgsP p = (ArgsP)__builtin_amdgcn_kernarg_segment_ptr(); asm volatile("" : "+s"(p)); return p; }
; #define TIDS() int lane_ = (int)__builtin_amdgcn_mbcnt_hi(~0u, __builtin_amdgcn_mbcnt_lo(~0u, 0u)); asm volatile("" : "+v"(lane_)); const int lane = lane_ & 63, wave = wave_s & 7, tid = wave * 64 + lane; const int G = gridDim.x, bx = blockIdx.x; (void)lane; (void)wave; (void)tid; (void)G; (void)bx
; __device__ __forceinline__ void convert_layer(ArgsP a, int L, int first, int stride, int lane) {
;     unsigned char* ws = a->ws;
;     bf16* WIN = (bf16*)(ws + WS_WIN); bf16* WOUT = (bf16*)(ws + WS_WOUT); bf16* WGU = (bf16*)(ws + WS_WGU); bf16* WDN = (bf16*)(ws + WS_WDN);
;     for (int r = first; r < I_L; r += stride) {
;         if (r < I_IN) transpose_item(a->in[3] + (size_t)L * D * INW, D, INW, WIN + (size_t)L * INW * D, a->in[2] + L * D, 1, 0, r, lane);
;         else if (r < I_IN + I_OUT) transpose_item(a->in[4] + (size_t)L * D * D, D, D, WOUT + (size_t)L * D * D, nullptr, 0, 0, r - I_IN, lane);
;         else if (r < I_IN + I_OUT + I_GU) transpose_item(a->in[18] + (size_t)L * D * GU, D, GU, WGU + (size_t)L * GU * D, a->in[17] + L * D, 2, 0, r - I_IN - I_OUT, lane);
;         else transpose_item(a->in[19] + (size_t)L * FFN * D, FFN, D, WDN + (size_t)L * D * FFN, nullptr, 0, 0, r - I_IN - I_OUT - I_GU, lane);
;     }
; }
; __device__ __forceinline__ void phase_A(unsigned char* lds, int wave_s, int L) {
;     ArgsP a = args_ptr(); TIDS(); unsigned char* ws = a->ws; const int j = L >> 1;
;     pg8::Gemm g{(bf16*)(ws + WS_XB), (bf16*)(ws + WS_WIN) + (size_t)L * INW * D, M, INW, D}; pg8::StaticOrder S; S.init(M, INW, G, bx);
;     pg8::EpiU E{(bf16*)(ws + WS_U), (const float*)(ws + WS_SS), L & 1, a->in[10] + j * 64, a->in[11] + j * 64, a->in[7] + L * 64, 0.125f * 1.4426950408889634f};
;     if (L + 1 < DEPTH && bx >= 128 && bx < 224) { convert_layer(args_ptr(), L + 1, (bx - 128) * NWAVES + wave, 96 * NWAVES, lane); asm volatile("s_waitcnt vmcnt(0)" ::: "memory"); }
;     pg8::gemm_phase<pg8::EpiU, pg8::StaticOrder, true, true>((pg8::PG8_LAS_T*)lds, g, S, E, tid);
.LBB0_677:
	s_or_b64 exec, exec, s[10:11]
	s_mov_b64 s[4:5], s[96:97]
	s_waitcnt lgkmcnt(0)
	s_barrier
	s_cmp_lt_u32 s2, 0xe0
	s_cbranch_scc1 .Lcx2_skip
	s_cmp_ge_u32 s2, 0xf8
	s_cbranch_scc1 .Lcx2_skip
	v_mov_b32_e32 v128, v2
	v_mov_b32_e32 v129, v3
	v_mov_b32_e32 v130, v64
	v_mov_b32_e32 v131, v65
	v_mov_b32_e32 v132, v66
	v_mov_b32_e32 v133, v67
	v_mov_b32_e32 v134, v68
	v_mov_b32_e32 v135, v69
	v_mov_b32_e32 v136, v70
	v_mov_b32_e32 v137, v71
	v_mov_b32_e32 v138, v72
	v_mov_b32_e32 v139, v73
	v_mov_b32_e32 v140, v74
	v_mov_b32_e32 v141, v75
	v_mov_b32_e32 v142, v76
	v_mov_b32_e32 v143, v77
	v_mov_b32_e32 v144, v78
	v_mov_b32_e32 v145, v79
	v_mov_b32_e32 v146, v81
	v_mov_b32_e32 v147, v82
	v_mov_b32_e32 v148, v83
	v_mov_b32_e32 v149, v84
	v_mov_b32_e32 v150, v85
	v_mov_b32_e32 v151, v86
	v_mov_b32_e32 v152, v87
	v_mov_b32_e32 v153, v88
	v_mov_b32_e32 v154, v89
	v_mov_b32_e32 v155, v90
	v_mov_b32_e32 v156, v91
	v_writelane_b32 v253, s4, 0
	v_writelane_b32 v253, s5, 1
	v_writelane_b32 v253, s6, 2
	v_writelane_b32 v253, s7, 3
	v_writelane_b32 v253, s34, 4
	v_writelane_b32 v253, s35, 5
	v_writelane_b32 v253, s36, 6
	v_writelane_b32 v253, s38, 7
	v_writelane_b32 v253, s39, 8
	v_writelane_b32 v253, s42, 9
	v_writelane_b32 v253, s43, 10
	v_writelane_b32 v253, s44, 11
	v_writelane_b32 v253, s46, 12
	v_writelane_b32 v253, s70, 13
	v_writelane_b32 v253, s71, 14
	v_writelane_b32 v253, s72, 15
	v_writelane_b32 v253, s86, 16
	v_writelane_b32 v253, s87, 17
	v_and_b32_e32 v80, 63, v201
	s_mov_b64 s[12:13], s[96:97]
	s_load_dwordx2 s[4:5], s[12:13], 0xa8
	v_readlane_b32 s1, v252, 2
	v_readlane_b32 s14, v252, 1
	s_nop 3
	s_add_i32 s1, s1, s14
	s_add_i32 s1, s1, 0x400
	v_lshlrev_b32_e32 v0, 2, v80
	s_waitcnt lgkmcnt(0)
	s_add_u32 s14, s4, 0x4e80000
	s_addc_u32 s15, s5, 0
	s_add_u32 s16, s4, 0x2800000
	s_addc_u32 s17, s5, 0
	s_add_u32 s18, s4, 0x1700000
	s_addc_u32 s19, s5, 0
	s_add_u32 s22, s4, 0x600000
	s_addc_u32 s23, s5, 0
	s_lshl_b32 s3, s1, 6
	v_and_b32_e32 v81, 0x80, v0
	v_or_b32_e32 v82, s3, v80
	s_lshl_b32 s26, s1, 5
	s_lshl_b32 s27, s1, 2
	v_mov_b32_e32 v13, 0
	s_movk_i32 s30, 0x7fff
	s_mov_b32 s31, 0xffff0000
	v_mov_b32_e32 v83, 0x1000
	v_mov_b32_e32 v84, 1
	s_mov_b32 s33, 0xa0f000
	s_mov_b32 s34, 0xa11000
	s_mov_b32 s35, 0xa14000
	s_mov_b32 s36, 0xa16000
	s_mov_b32 s37, 0xa19000
	s_mov_b32 s38, 0xa1b000
	s_mov_b32 s39, 0xa1e000
	s_mov_b32 s40, 0xa20000
	s_mov_b32 s41, 0xa23000
	s_mov_b32 s42, 0xa25000
	s_mov_b32 s43, 0xa28000
	s_mov_b32 s44, 0xa2a000
	s_mov_b32 s45, 0xa2d000
	s_mov_b32 s46, 0xa2f000
	s_mov_b32 s47, 0xa32000
	s_mov_b32 s48, 0xa34000
	s_mov_b32 s49, 0xa37000
	s_mov_b32 s50, 0xa39000
	s_mov_b32 s51, 0xa3c000
	s_mov_b32 s52, 0xa3e000
	s_mov_b32 s53, 0xa41000
	s_mov_b32 s54, 0xa43000
	s_mov_b32 s55, 0xa46000
	s_mov_b32 s56, 0xa48000
	s_mov_b32 s57, 0xa4b000
	s_mov_b32 s58, 0xa4d000
	s_mov_b32 s59, 0xa50000
	s_mov_b32 s60, 0xa52000
	s_mov_b32 s61, 0xa55000
	s_mov_b32 s62, 0xa57000
	s_mov_b32 s63, 0xa5a000
	s_mov_b32 s64, 0xa5c000
	s_mov_b32 s65, 0xa5f000
	s_mov_b32 s66, 0xa61000
	s_mov_b32 s67, 0xa64000
	s_mov_b32 s68, 0xa66000
	s_mov_b32 s69, 0xa69000
	s_mov_b32 s70, 0xa6b000
	s_mov_b32 s71, 0xa6e000
	s_mov_b32 s72, 0xa70000
	s_mov_b32 s73, 0xa73000
	s_mov_b32 s74, 0xa75000
	s_mov_b32 s75, 0xa78000
	s_mov_b32 s76, 0xa7a000
	s_mov_b32 s77, 0xa7d000
	s_mov_b32 s78, 0xa7f000
	s_mov_b32 s79, 0xa82000
	s_mov_b32 s80, 0xa84000
	s_mov_b32 s81, 0xa87000
	s_mov_b32 s82, 0xa89000
	s_mov_b32 s83, 0xa8c000
	s_mov_b32 s84, 0xa8e000
	s_mov_b32 s85, 0xa91000
	s_mov_b32 s86, 0xa93000
	s_mov_b32 s87, 0xa96000
	s_mov_b32 s88, 0xa98000
	s_mov_b32 s89, 0xa9b000
	s_mov_b32 s90, 0xa9d000
	s_mov_b32 s25, 0
	s_branch .Lcx2_89

; __device__ __forceinline__ unsigned pk2(float lo, float hi) { return f2bf(lo) | (f2bf(hi) << 16); }
; __device__ __forceinline__ void transpose_item(const float* __restrict__ W, int K, int N, bf16* __restrict__ WT, const float* __restrict__ ksc, int mode, int row_off, int item, int lane) {
;     const int nblk = N / 64, kb = item / nblk, nb = item % nblk, k0 = 64 * kb, n = 64 * nb + lane;
;     const float* src = W + (size_t)k0 * N + n;
;     float v[64];
; #pragma unroll
;     for (int i = 0; i < 64; ++i) v[i] = __builtin_nontemporal_load(src + (size_t)i * N);
;     if (ksc) {
; #pragma unroll
;         for (int i = 0; i < 64; ++i) v[i] *= ksc[k0 + i];
;     }
;     bf16* dst = WT + (size_t)(row_off + map_row(n, mode)) * K + k0;
; #pragma unroll
;     for (int j = 0; j < 8; ++j) { v4u o; o.x = pk2(v[8 * j], v[8 * j + 1]); o.y = pk2(v[8 * j + 2], v[8 * j + 3]); o.z = pk2(v[8 * j + 4], v[8 * j + 5]); o.w = pk2(v[8 * j + 6], v[8 * j + 7]);
;         *(v4u*)(dst + 8 * j) = o; }
; __device__ __forceinline__ void convert_layer(ArgsP a, int L, int first, int stride, int lane) {
;     ...
;     for (int r = first; r < I_L; r += stride) {
;         if (r < I_IN) transpose_item(a->in[3] + (size_t)L * D * INW, D, INW, WIN + (size_t)L * INW * D, a->in[2] + L * D, 1, 0, r, lane);
;         else if (r < I_IN + I_OUT) transpose_item(a->in[4] + (size_t)L * D * D, D, D, WOUT + (size_t)L * D * D, nullptr, 0, 0, r - I_IN, lane);
;         else if (r < I_IN + I_OUT + I_GU) transpose_item(a->in[18] + (size_t)L * D * GU, D, GU, WGU + (size_t)L * GU * D, a->in[17] + L * D, 2, 0, r - I_IN - I_OUT, lane);
;         else transpose_item(a->in[19] + (size_t)L * FFN * D, FFN, D, WDN + (size_t)L * D * FFN, nullptr, 0, 0, r - I_IN - I_OUT - I_GU, lane);
;     }
.Lcx2_88:
	s_add_i32 s4, s1, 0x400
	s_add_i32 s26, s26, 0x8000
	s_add_i32 s27, s27, 0x1000
	s_add_i32 s3, s3, 0x10000
	v_add_u32_e32 v82, 0x10000, v82
	s_cmpk_lt_i32 s1, 0x0
	s_mov_b32 s1, s4
	global_store_dwordx4 v[78:79], v[0:3], off offset:112
	s_cbranch_scc0 .Lcx2_108

; __device__ __forceinline__ ArgsP args_ptr() { ArgsP p = (ArgsP)__builtin_amdgcn_kernarg_segment_ptr(); asm volatile("" : "+s"(p)); return p; }
; #define TIDS() int lane_ = (int)__builtin_amdgcn_mbcnt_hi(~0u, __builtin_amdgcn_mbcnt_lo(~0u, 0u)); asm volatile("" : "+v"(lane_)); const int lane = lane_ & 63, wave = wave_s & 7, tid = wave * 64 + lane; const int G = gridDim.x, bx = blockIdx.x; (void)lane; (void)wave; (void)tid; (void)G; (void)bx
; __device__ __forceinline__ void convert_layer(ArgsP a, int L, int first, int stride, int lane) {
;     unsigned char* ws = a->ws;
;     bf16* WIN = (bf16*)(ws + WS_WIN); bf16* WOUT = (bf16*)(ws + WS_WOUT); bf16* WGU = (bf16*)(ws + WS_WGU); bf16* WDN = (bf16*)(ws + WS_WDN);
;     for (int r = first; r < I_L; r += stride) {
;         if (r < I_IN) transpose_item(a->in[3] + (size_t)L * D * INW, D, INW, WIN + (size_t)L * INW * D, a->in[2] + L * D, 1, 0, r, lane);
;         else if (r < I_IN + I_OUT) transpose_item(a->in[4] + (size_t)L * D * D, D, D, WOUT + (size_t)L * D * D, nullptr, 0, 0, r - I_IN, lane);
;         else if (r < I_IN + I_OUT + I_GU) transpose_item(a->in[18] + (size_t)L * D * GU, D, GU, WGU + (size_t)L * GU * D, a->in[17] + L * D, 2, 0, r - I_IN - I_OUT, lane);
;         else transpose_item(a->in[19] + (size_t)L * FFN * D, FFN, D, WDN + (size_t)L * D * FFN, nullptr, 0, 0, r - I_IN - I_OUT - I_GU, lane);
;     }
; }
; __device__ __forceinline__ void phase_A(unsigned char* lds, int wave_s, int L) {
;     ArgsP a = args_ptr(); TIDS(); unsigned char* ws = a->ws; const int j = L >> 1;
;     pg8::Gemm g{(bf16*)(ws + WS_XB), (bf16*)(ws + WS_WIN) + (size_t)L * INW * D, M, INW, D}; pg8::StaticOrder S; S.init(M, INW, G, bx);
;     pg8::EpiU E{(bf16*)(ws + WS_U), (const float*)(ws + WS_SS), L & 1, a->in[10] + j * 64, a->in[11] + j * 64, a->in[7] + L * 64, 0.125f * 1.4426950408889634f};
;     if (L + 1 < DEPTH && bx >= 128 && bx < 224) { convert_layer(args_ptr(), L + 1, (bx - 128) * NWAVES + wave, 96 * NWAVES, lane); asm volatile("s_waitcnt vmcnt(0)" ::: "memory"); }
;     pg8::gemm_phase<pg8::EpiU, pg8::StaticOrder, true, true>((pg8::PG8_LAS_T*)lds, g, S, E, tid);
.Lcx2_108:
	s_waitcnt vmcnt(0)
	v_mov_b32_e32 v2, v128
	v_mov_b32_e32 v3, v129
	v_mov_b32_e32 v64, v130
	v_mov_b32_e32 v65, v131
	v_mov_b32_e32 v66, v132
	v_mov_b32_e32 v67, v133
	v_mov_b32_e32 v68, v134
	v_mov_b32_e32 v69, v135
	v_mov_b32_e32 v70, v136
	v_mov_b32_e32 v71, v137
	v_mov_b32_e32 v72, v138
	v_mov_b32_e32 v73, v139
	v_mov_b32_e32 v74, v140
	v_mov_b32_e32 v75, v141
	v_mov_b32_e32 v76, v142
	v_mov_b32_e32 v77, v143
	v_mov_b32_e32 v78, v144
	v_mov_b32_e32 v79, v145
	v_mov_b32_e32 v81, v146
	v_mov_b32_e32 v82, v147
	v_mov_b32_e32 v83, v148
	v_mov_b32_e32 v84, v149
	v_mov_b32_e32 v85, v150
	v_mov_b32_e32 v86, v151
	v_mov_b32_e32 v87, v152
	v_mov_b32_e32 v88, v153
	v_mov_b32_e32 v89, v154
	v_mov_b32_e32 v90, v155
	v_mov_b32_e32 v91, v156
	v_readlane_b32 s4, v253, 0
	v_readlane_b32 s5, v253, 1
	v_readlane_b32 s6, v253, 2
	v_readlane_b32 s7, v253, 3
	v_readlane_b32 s34, v253, 4
	v_readlane_b32 s35, v253, 5
	v_readlane_b32 s36, v253, 6
	v_readlane_b32 s38, v253, 7
	v_readlane_b32 s39, v253, 8
	v_readlane_b32 s42, v253, 9
	v_readlane_b32 s43, v253, 10
	v_readlane_b32 s44, v253, 11
	v_readlane_b32 s46, v253, 12
	v_readlane_b32 s70, v253, 13
	v_readlane_b32 s71, v253, 14
	v_readlane_b32 s72, v253, 15
	v_readlane_b32 s86, v253, 16
	v_readlane_b32 s87, v253, 17
	s_nop 4
.Lcx2_skip:
	v_mov_b32_e32 v0, v201
	s_load_dwordx2 s[10:11], s[4:5], 0xa8
	s_load_dwordx2 s[12:13], s[4:5], 0x38
	s_load_dwordx4 s[16:19], s[4:5], 0x50
	v_cndmask_b32_e64 v1, 0, 1, s[20:21]
	v_cmp_ne_u32_e64 s[4:5], 1, v1
	s_andn2_b64 vcc, exec, s[20:21]
	v_and_b32_e32 v80, 63, v0
	v_writelane_b32 v252, s4, 12
	s_nop 1
	v_writelane_b32 v252, s5, 13
	s_cbranch_vccnz .LBB0_701
	s_mov_b64 s[24:25], s[96:97]
	s_load_dwordx2 s[4:5], s[24:25], 0xa8
	v_readlane_b32 s1, v252, 2
	s_add_i32 s1, s1, s86
	s_addk_i32 s1, 0xfc00
	v_lshlrev_b32_e32 v0, 2, v80
	s_waitcnt lgkmcnt(0)
	s_add_u32 s26, s4, 0x5400000
	s_addc_u32 s27, s5, 0
	s_add_u32 s34, s4, 0x3300000
	s_addc_u32 s35, s5, 0
	s_add_u32 s36, s4, 0x1900000
	s_addc_u32 s37, s5, 0
	s_add_u32 s38, s4, 0xb00000
	s_addc_u32 s39, s5, 0
	s_lshl_b32 s3, s1, 6
	v_and_b32_e32 v81, 0x80, v0
	v_or_b32_e32 v82, s3, v80
	s_lshl_b32 s4, s1, 5
	s_lshl_b32 s5, s1, 2
	v_mov_b32_e32 v13, 0
	s_movk_i32 s30, 0x7fff
	s_mov_b32 s31, 0xffff0000
	v_mov_b32_e32 v83, 0x2000
	v_mov_b32_e32 v84, 1
	s_mov_b32 s33, 0x1439000
	s_mov_b32 s44, 0x143c000
	s_mov_b32 s45, 0x143e000
	s_mov_b32 s46, 0x1441000
	s_mov_b32 s47, 0x1443000
	s_mov_b32 s48, 0x1446000
	s_mov_b32 s49, 0x1448000
	s_mov_b32 s50, 0x144b000
	s_mov_b32 s51, 0x144d000
	s_mov_b32 s52, 0x1450000
	s_mov_b32 s53, 0x1452000
	s_mov_b32 s54, 0x1455000
	s_mov_b32 s55, 0x1457000
	s_mov_b32 s56, 0x145a000
	s_mov_b32 s57, 0x145c000
	s_mov_b32 s58, 0x145f000
	s_mov_b32 s59, 0x1461000
	s_mov_b32 s60, 0x1464000
	s_mov_b32 s61, 0x1466000
	s_mov_b32 s62, 0x1469000
	s_mov_b32 s63, 0x146b000
	s_mov_b32 s64, 0x146e000
	s_mov_b32 s65, 0x1470000
	s_mov_b32 s66, 0x1473000
	s_mov_b32 s67, 0x1475000
	s_mov_b32 s68, 0x1478000
	s_mov_b32 s69, 0x147a000
	s_mov_b32 s70, 0x147d000
	s_mov_b32 s71, 0x147f000
	s_mov_b32 s72, 0x1482000
	s_mov_b32 s73, 0x1484000
	s_mov_b32 s74, 0x1487000
	s_mov_b32 s75, 0x1489000
	s_mov_b32 s76, 0x148c000
	s_mov_b32 s77, 0x148e000
	s_mov_b32 s78, 0x1491000
	s_mov_b32 s79, 0x1493000
	s_mov_b32 s80, 0x1496000
	s_mov_b32 s81, 0x1498000
	s_mov_b32 s82, 0x149b000
	s_mov_b32 s83, 0x149d000
	s_mov_b32 s41, 0
	s_branch .LBB0_681

; __device__ __forceinline__ ArgsP args_ptr() { ArgsP p = (ArgsP)__builtin_amdgcn_kernarg_segment_ptr(); asm volatile("" : "+s"(p)); return p; }
; __device__ __forceinline__ void convert_layer(ArgsP a, int L, int first, int stride, int lane) {
;     ...
;     for (int r = first; r < I_L; r += stride) {
;         if (r < I_IN) transpose_item(a->in[3] + (size_t)L * D * INW, D, INW, WIN + (size_t)L * INW * D, a->in[2] + L * D, 1, 0, r, lane);
;         else if (r < I_IN + I_OUT) transpose_item(a->in[4] + (size_t)L * D * D, D, D, WOUT + (size_t)L * D * D, nullptr, 0, 0, r - I_IN, lane);
;         else if (r < I_IN + I_OUT + I_GU) transpose_item(a->in[18] + (size_t)L * D * GU, D, GU, WGU + (size_t)L * GU * D, a->in[17] + L * D, 2, 0, r - I_IN - I_OUT, lane);
;         else transpose_item(a->in[19] + (size_t)L * FFN * D, FFN, D, WDN + (size_t)L * D * FFN, nullptr, 0, 0, r - I_IN - I_OUT - I_GU, lane);
;     }
; __device__ __forceinline__ void phase_A(unsigned char* lds, int wave_s, int L) {
;     ...
;     if (L + 1 < DEPTH && bx >= 128 && bx < 224) { convert_layer(args_ptr(), L + 1, (bx - 128) * NWAVES + wave, 96 * NWAVES, lane); asm volatile("s_waitcnt vmcnt(0)" ::: "memory"); }
.LBB0_680:
	s_add_i32 s14, s1, 0x300
	s_addk_i32 s4, 0x6000
	s_addk_i32 s5, 0xc00
	s_add_i32 s3, s3, 0xc000
	v_add_u32_e32 v82, 0xc000, v82
	s_cmpk_lt_i32 s1, 0
	s_mov_b32 s1, s14
	global_store_dwordx4 v[78:79], v[0:3], off offset:112
	s_cbranch_scc0 .LBB0_700

; __device__ __forceinline__ ArgsP args_ptr() { ArgsP p = (ArgsP)__builtin_amdgcn_kernarg_segment_ptr(); asm volatile("" : "+s"(p)); return p; }
; #define TIDS() int lane_ = (int)__builtin_amdgcn_mbcnt_hi(~0u, __builtin_amdgcn_mbcnt_lo(~0u, 0u)); asm volatile("" : "+v"(lane_)); const int lane = lane_ & 63, wave = wave_s & 7, tid = wave * 64 + lane; const int G = gridDim.x, bx = blockIdx.x; (void)lane; (void)wave; (void)tid; (void)G; (void)bx
; __device__ __forceinline__ void convert_layer(ArgsP a, int L, int first, int stride, int lane) {
;     unsigned char* ws = a->ws;
;     bf16* WIN = (bf16*)(ws + WS_WIN); bf16* WOUT = (bf16*)(ws + WS_WOUT); bf16* WGU = (bf16*)(ws + WS_WGU); bf16* WDN = (bf16*)(ws + WS_WDN);
;     for (int r = first; r < I_L; r += stride) {
;         if (r < I_IN) transpose_item(a->in[3] + (size_t)L * D * INW, D, INW, WIN + (size_t)L * INW * D, a->in[2] + L * D, 1, 0, r, lane);
;         else if (r < I_IN + I_OUT) transpose_item(a->in[4] + (size_t)L * D * D, D, D, WOUT + (size_t)L * D * D, nullptr, 0, 0, r - I_IN, lane);
;         else if (r < I_IN + I_OUT + I_GU) transpose_item(a->in[18] + (size_t)L * D * GU, D, GU, WGU + (size_t)L * GU * D, a->in[17] + L * D, 2, 0, r - I_IN - I_OUT, lane);
;         else transpose_item(a->in[19] + (size_t)L * FFN * D, FFN, D, WDN + (size_t)L * D * FFN, nullptr, 0, 0, r - I_IN - I_OUT - I_GU, lane);
;     }
; }
; __device__ __forceinline__ void phase_D(unsigned char* lds, int wave_s, int L) {
;     ArgsP a = args_ptr(); TIDS(); unsigned char* ws = a->ws;
;     pg8::Gemm g{(bf16*)(ws + WS_XB), (bf16*)(ws + WS_WGU) + (size_t)L * GU * D, M, GU, D}; pg8::StaticOrder S; S.init(M, GU, G, bx);
;     pg8::EpiSwi E{(bf16*)(ws + WS_ACT), (const float*)(ws + WS_SS)};
;     pg8::gemm_phase<pg8::EpiSwi, pg8::StaticOrder, true, true>((pg8::PG8_LAS_T*)lds, g, S, E, tid);
.LBB0_987:
	s_or_b64 exec, exec, s[12:13]
	v_readlane_b32 s16, v252, 15
	v_readlane_b32 s17, v252, 16
	s_waitcnt lgkmcnt(0)
	v_mov_b32_e32 v0, v201
	s_barrier
	s_cmp_lt_u32 s2, 0x80
	s_cbranch_scc1 .Lcx3_skip
	s_cmp_ge_u32 s2, 0x100
	s_cbranch_scc1 .Lcx3_skip
	v_mov_b32_e32 v128, v0
	v_mov_b32_e32 v129, v1
	v_mov_b32_e32 v130, v2
	v_mov_b32_e32 v131, v3
	v_mov_b32_e32 v132, v64
	v_mov_b32_e32 v133, v65
	v_mov_b32_e32 v134, v66
	v_mov_b32_e32 v135, v67
	v_mov_b32_e32 v136, v68
	v_mov_b32_e32 v137, v69
	v_mov_b32_e32 v138, v70
	v_mov_b32_e32 v139, v71
	v_mov_b32_e32 v140, v72
	v_mov_b32_e32 v141, v73
	v_mov_b32_e32 v142, v74
	v_mov_b32_e32 v143, v75
	v_mov_b32_e32 v144, v76
	v_mov_b32_e32 v145, v77
	v_mov_b32_e32 v146, v78
	v_mov_b32_e32 v147, v79
	v_mov_b32_e32 v148, v81
	v_mov_b32_e32 v149, v82
	v_mov_b32_e32 v150, v83
	v_mov_b32_e32 v151, v84
	v_mov_b32_e32 v152, v85
	v_mov_b32_e32 v153, v86
	v_mov_b32_e32 v154, v87
	v_mov_b32_e32 v155, v88
	v_mov_b32_e32 v156, v89
	v_mov_b32_e32 v157, v90
	v_mov_b32_e32 v158, v91
	v_writelane_b32 v253, s1, 0
	v_writelane_b32 v253, s22, 1
	v_writelane_b32 v253, s30, 2
	v_writelane_b32 v253, s31, 3
	v_writelane_b32 v253, s34, 4
	v_writelane_b32 v253, s35, 5
	v_writelane_b32 v253, s36, 6
	v_writelane_b32 v253, s37, 7
	v_writelane_b32 v253, s38, 8
	v_writelane_b32 v253, s39, 9
	v_writelane_b32 v253, s41, 10
	v_writelane_b32 v253, s44, 11
	v_writelane_b32 v253, s45, 12
	v_writelane_b32 v253, s46, 13
	v_writelane_b32 v253, s47, 14
	v_writelane_b32 v253, s48, 15
	v_writelane_b32 v253, s49, 16
	v_writelane_b32 v253, s50, 17
	v_writelane_b32 v253, s51, 18
	v_writelane_b32 v253, s52, 19
	v_writelane_b32 v253, s54, 20
	v_writelane_b32 v253, s63, 21
	v_writelane_b32 v253, s64, 22
	v_writelane_b32 v253, s65, 23
	v_writelane_b32 v253, s70, 24
	v_writelane_b32 v253, s71, 25
	v_writelane_b32 v253, s72, 26
	v_writelane_b32 v253, s74, 27
	v_writelane_b32 v253, s75, 28
	v_writelane_b32 v253, s77, 29
	v_writelane_b32 v253, s82, 30
	v_writelane_b32 v253, s83, 31
	v_writelane_b32 v253, s84, 32
	v_writelane_b32 v253, s85, 33
	v_and_b32_e32 v80, 63, v201
	v_readlane_b32 s24, v252, 15
	v_readlane_b32 s25, v252, 16
	s_nop 3
	s_load_dwordx2 s[4:5], s[24:25], 0xa8
	v_readlane_b32 s1, v252, 2
	v_readlane_b32 s14, v252, 1
	s_nop 3
	s_add_i32 s1, s1, s14
	s_add_i32 s1, s1, 0xffffff00
	v_lshlrev_b32_e32 v0, 2, v80
	s_waitcnt lgkmcnt(0)
	s_add_u32 s26, s4, 0x5400000
	s_addc_u32 s27, s5, 0
	s_add_u32 s34, s4, 0x3300000
	s_addc_u32 s35, s5, 0
	s_add_u32 s36, s4, 0x1900000
	s_addc_u32 s37, s5, 0
	s_add_u32 s38, s4, 0xb00000
	s_addc_u32 s39, s5, 0
	s_lshl_b32 s3, s1, 6
	v_and_b32_e32 v81, 0x80, v0
	v_or_b32_e32 v82, s3, v80
	s_lshl_b32 s4, s1, 5
	s_lshl_b32 s5, s1, 2
	v_mov_b32_e32 v13, 0
	s_movk_i32 s30, 0x7fff
	s_mov_b32 s31, 0xffff0000
	v_mov_b32_e32 v83, 0x2000
	v_mov_b32_e32 v84, 1
	s_mov_b32 s33, 0x1439000
	s_mov_b32 s44, 0x143c000
	s_mov_b32 s45, 0x143e000
	s_mov_b32 s46, 0x1441000
	s_mov_b32 s47, 0x1443000
	s_mov_b32 s48, 0x1446000
	s_mov_b32 s49, 0x1448000
	s_mov_b32 s50, 0x144b000
	s_mov_b32 s51, 0x144d000
	s_mov_b32 s52, 0x1450000
	s_mov_b32 s53, 0x1452000
	s_mov_b32 s54, 0x1455000
	s_mov_b32 s55, 0x1457000
	s_mov_b32 s56, 0x145a000
	s_mov_b32 s57, 0x145c000
	s_mov_b32 s58, 0x145f000
	s_mov_b32 s59, 0x1461000
	s_mov_b32 s60, 0x1464000
	s_mov_b32 s61, 0x1466000
	s_mov_b32 s62, 0x1469000
	s_mov_b32 s63, 0x146b000
	s_mov_b32 s64, 0x146e000
	s_mov_b32 s65, 0x1470000
	s_mov_b32 s66, 0x1473000
	s_mov_b32 s67, 0x1475000
	s_mov_b32 s68, 0x1478000
	s_mov_b32 s69, 0x147a000
	s_mov_b32 s70, 0x147d000
	s_mov_b32 s71, 0x147f000
	s_mov_b32 s72, 0x1482000
	s_mov_b32 s73, 0x1484000
	s_mov_b32 s74, 0x1487000
	s_mov_b32 s75, 0x1489000
	s_mov_b32 s76, 0x148c000
	s_mov_b32 s77, 0x148e000
	s_mov_b32 s78, 0x1491000
	s_mov_b32 s79, 0x1493000
	s_mov_b32 s80, 0x1496000
	s_mov_b32 s81, 0x1498000
	s_mov_b32 s82, 0x149b000
	s_mov_b32 s83, 0x149d000
	s_mov_b32 s41, 0
	s_branch .Lcx3_681

; __device__ __forceinline__ unsigned pk2(float lo, float hi) { return f2bf(lo) | (f2bf(hi) << 16); }
; __device__ __forceinline__ void transpose_item(const float* __restrict__ W, int K, int N, bf16* __restrict__ WT, const float* __restrict__ ksc, int mode, int row_off, int item, int lane) {
;     const int nblk = N / 64, kb = item / nblk, nb = item % nblk, k0 = 64 * kb, n = 64 * nb + lane;
;     const float* src = W + (size_t)k0 * N + n;
;     float v[64];
; #pragma unroll
;     for (int i = 0; i < 64; ++i) v[i] = __builtin_nontemporal_load(src + (size_t)i * N);
;     if (ksc) {
; #pragma unroll
;         for (int i = 0; i < 64; ++i) v[i] *= ksc[k0 + i];
;     }
;     bf16* dst = WT + (size_t)(row_off + map_row(n, mode)) * K + k0;
; #pragma unroll
;     for (int j = 0; j < 8; ++j) { v4u o; o.x = pk2(v[8 * j], v[8 * j + 1]); o.y = pk2(v[8 * j + 2], v[8 * j + 3]); o.z = pk2(v[8 * j + 4], v[8 * j + 5]); o.w = pk2(v[8 * j + 6], v[8 * j + 7]);
;         *(v4u*)(dst + 8 * j) = o; }
; __device__ __forceinline__ void convert_layer(ArgsP a, int L, int first, int stride, int lane) {
;     ...
;     for (int r = first; r < I_L; r += stride) {
;         if (r < I_IN) transpose_item(a->in[3] + (size_t)L * D * INW, D, INW, WIN + (size_t)L * INW * D, a->in[2] + L * D, 1, 0, r, lane);
;         else if (r < I_IN + I_OUT) transpose_item(a->in[4] + (size_t)L * D * D, D, D, WOUT + (size_t)L * D * D, nullptr, 0, 0, r - I_IN, lane);
;         else if (r < I_IN + I_OUT + I_GU) transpose_item(a->in[18] + (size_t)L * D * GU, D, GU, WGU + (size_t)L * GU * D, a->in[17] + L * D, 2, 0, r - I_IN - I_OUT, lane);
;         else transpose_item(a->in[19] + (size_t)L * FFN * D, FFN, D, WDN + (size_t)L * D * FFN, nullptr, 0, 0, r - I_IN - I_OUT - I_GU, lane);
;     }
.Lcx3_680:
	s_add_i32 s14, s1, 0x400
	s_add_i32 s4, s4, 0x8000
	s_add_i32 s5, s5, 0x1000
	s_add_i32 s3, s3, 0x10000
	v_add_u32_e32 v82, 0x10000, v82
	s_cmpk_lt_i32 s1, 0x700
	s_mov_b32 s1, s14
	global_store_dwordx4 v[78:79], v[0:3], off offset:112
	s_cbranch_scc0 .Lcx3_700

; __device__ __forceinline__ ArgsP args_ptr() { ArgsP p = (ArgsP)__builtin_amdgcn_kernarg_segment_ptr(); asm volatile("" : "+s"(p)); return p; }
; #define TIDS() int lane_ = (int)__builtin_amdgcn_mbcnt_hi(~0u, __builtin_amdgcn_mbcnt_lo(~0u, 0u)); asm volatile("" : "+v"(lane_)); const int lane = lane_ & 63, wave = wave_s & 7, tid = wave * 64 + lane; const int G = gridDim.x, bx = blockIdx.x; (void)lane; (void)wave; (void)tid; (void)G; (void)bx
; __device__ __forceinline__ void convert_layer(ArgsP a, int L, int first, int stride, int lane) {
;     unsigned char* ws = a->ws;
;     bf16* WIN = (bf16*)(ws + WS_WIN); bf16* WOUT = (bf16*)(ws + WS_WOUT); bf16* WGU = (bf16*)(ws + WS_WGU); bf16* WDN = (bf16*)(ws + WS_WDN);
;     for (int r = first; r < I_L; r += stride) {
;         if (r < I_IN) transpose_item(a->in[3] + (size_t)L * D * INW, D, INW, WIN + (size_t)L * INW * D, a->in[2] + L * D, 1, 0, r, lane);
;         else if (r < I_IN + I_OUT) transpose_item(a->in[4] + (size_t)L * D * D, D, D, WOUT + (size_t)L * D * D, nullptr, 0, 0, r - I_IN, lane);
;         else if (r < I_IN + I_OUT + I_GU) transpose_item(a->in[18] + (size_t)L * D * GU, D, GU, WGU + (size_t)L * GU * D, a->in[17] + L * D, 2, 0, r - I_IN - I_OUT, lane);
;         else transpose_item(a->in[19] + (size_t)L * FFN * D, FFN, D, WDN + (size_t)L * D * FFN, nullptr, 0, 0, r - I_IN - I_OUT - I_GU, lane);
;     }
; }
; __device__ __forceinline__ void phase_A(unsigned char* lds, int wave_s, int L) {
;     ArgsP a = args_ptr(); TIDS(); unsigned char* ws = a->ws; const int j = L >> 1;
;     pg8::Gemm g{(bf16*)(ws + WS_XB), (bf16*)(ws + WS_WIN) + (size_t)L * INW * D, M, INW, D}; pg8::StaticOrder S; S.init(M, INW, G, bx);
;     pg8::EpiU E{(bf16*)(ws + WS_U), (const float*)(ws + WS_SS), L & 1, a->in[10] + j * 64, a->in[11] + j * 64, a->in[7] + L * 64, 0.125f * 1.4426950408889634f};
;     if (L + 1 < DEPTH && bx >= 128 && bx < 224) { convert_layer(args_ptr(), L + 1, (bx - 128) * NWAVES + wave, 96 * NWAVES, lane); asm volatile("s_waitcnt vmcnt(0)" ::: "memory"); }
;     pg8::gemm_phase<pg8::EpiU, pg8::StaticOrder, true, true>((pg8::PG8_LAS_T*)lds, g, S, E, tid);
.LBB0_1153:
	s_or_b64 exec, exec, s[16:17]
	v_readlane_b32 s12, v252, 15
	v_readlane_b32 s13, v252, 16
	s_waitcnt lgkmcnt(0)
	s_barrier
	s_cmp_lt_u32 s2, 0xe0
	s_cbranch_scc1 .Lcx4_skip
	s_cmp_ge_u32 s2, 0xf8
	s_cbranch_scc1 .Lcx4_skip
	v_mov_b32_e32 v128, v1
	v_mov_b32_e32 v129, v2
	v_mov_b32_e32 v130, v3
	v_mov_b32_e32 v131, v64
	v_mov_b32_e32 v132, v65
	v_mov_b32_e32 v133, v66
	v_mov_b32_e32 v134, v67
	v_mov_b32_e32 v135, v68
	v_mov_b32_e32 v136, v69
	v_mov_b32_e32 v137, v70
	v_mov_b32_e32 v138, v71
	v_mov_b32_e32 v139, v72
	v_mov_b32_e32 v140, v73
	v_mov_b32_e32 v141, v74
	v_mov_b32_e32 v142, v75
	v_mov_b32_e32 v143, v76
	v_mov_b32_e32 v144, v77
	v_mov_b32_e32 v145, v78
	v_mov_b32_e32 v146, v79
	v_mov_b32_e32 v147, v81
	v_mov_b32_e32 v148, v82
	v_mov_b32_e32 v149, v83
	v_mov_b32_e32 v150, v84
	v_mov_b32_e32 v151, v85
	v_mov_b32_e32 v152, v86
	v_mov_b32_e32 v153, v87
	v_mov_b32_e32 v154, v88
	v_mov_b32_e32 v155, v89
	v_mov_b32_e32 v156, v90
	v_mov_b32_e32 v157, v91
	v_writelane_b32 v253, s1, 0
	v_writelane_b32 v253, s30, 1
	v_writelane_b32 v253, s31, 2
	v_writelane_b32 v253, s34, 3
	v_writelane_b32 v253, s35, 4
	v_writelane_b32 v253, s36, 5
	v_writelane_b32 v253, s37, 6
	v_writelane_b32 v253, s38, 7
	v_writelane_b32 v253, s39, 8
	v_writelane_b32 v253, s41, 9
	v_writelane_b32 v253, s44, 10
	v_writelane_b32 v253, s45, 11
	v_writelane_b32 v253, s46, 12
	v_writelane_b32 v253, s47, 13
	v_writelane_b32 v253, s48, 14
	v_writelane_b32 v253, s49, 15
	v_writelane_b32 v253, s50, 16
	v_writelane_b32 v253, s52, 17
	v_writelane_b32 v253, s63, 18
	v_writelane_b32 v253, s64, 19
	v_writelane_b32 v253, s65, 20
	v_writelane_b32 v253, s74, 21
	v_writelane_b32 v253, s75, 22
	v_writelane_b32 v253, s77, 23
	v_writelane_b32 v253, s82, 24
	v_writelane_b32 v253, s83, 25
	v_writelane_b32 v253, s84, 26
	v_writelane_b32 v253, s85, 27
	v_and_b32_e32 v80, 63, v201
	v_readlane_b32 s24, v252, 15
	v_readlane_b32 s25, v252, 16
	s_nop 3
	s_load_dwordx2 s[4:5], s[24:25], 0xa8
	v_readlane_b32 s1, v252, 2
	v_readlane_b32 s14, v252, 1
	s_nop 3
	s_add_i32 s1, s1, s14
	s_add_i32 s1, s1, 0x400
	v_lshlrev_b32_e32 v0, 2, v80
	s_waitcnt lgkmcnt(0)
	s_add_u32 s26, s4, 0x5400000
	s_addc_u32 s27, s5, 0
	s_add_u32 s34, s4, 0x3300000
	s_addc_u32 s35, s5, 0
	s_add_u32 s36, s4, 0x1900000
	s_addc_u32 s37, s5, 0
	s_add_u32 s38, s4, 0xb00000
	s_addc_u32 s39, s5, 0
	s_lshl_b32 s3, s1, 6
	v_and_b32_e32 v81, 0x80, v0
	v_or_b32_e32 v82, s3, v80
	s_lshl_b32 s4, s1, 5
	s_lshl_b32 s5, s1, 2
	v_mov_b32_e32 v13, 0
	s_movk_i32 s30, 0x7fff
	s_mov_b32 s31, 0xffff0000
	v_mov_b32_e32 v83, 0x2000
	v_mov_b32_e32 v84, 1
	s_mov_b32 s33, 0x1439000
	s_mov_b32 s44, 0x143c000
	s_mov_b32 s45, 0x143e000
	s_mov_b32 s46, 0x1441000
	s_mov_b32 s47, 0x1443000
	s_mov_b32 s48, 0x1446000
	s_mov_b32 s49, 0x1448000
	s_mov_b32 s50, 0x144b000
	s_mov_b32 s51, 0x144d000
	s_mov_b32 s52, 0x1450000
	s_mov_b32 s53, 0x1452000
	s_mov_b32 s54, 0x1455000
	s_mov_b32 s55, 0x1457000
	s_mov_b32 s56, 0x145a000
	s_mov_b32 s57, 0x145c000
	s_mov_b32 s58, 0x145f000
	s_mov_b32 s59, 0x1461000
	s_mov_b32 s60, 0x1464000
	s_mov_b32 s61, 0x1466000
	s_mov_b32 s62, 0x1469000
	s_mov_b32 s63, 0x146b000
	s_mov_b32 s64, 0x146e000
	s_mov_b32 s65, 0x1470000
	s_mov_b32 s66, 0x1473000
	s_mov_b32 s67, 0x1475000
	s_mov_b32 s68, 0x1478000
	s_mov_b32 s69, 0x147a000
	s_mov_b32 s70, 0x147d000
	s_mov_b32 s71, 0x147f000
	s_mov_b32 s72, 0x1482000
	s_mov_b32 s73, 0x1484000
	s_mov_b32 s74, 0x1487000
	s_mov_b32 s75, 0x1489000
	s_mov_b32 s76, 0x148c000
	s_mov_b32 s77, 0x148e000
	s_mov_b32 s78, 0x1491000
	s_mov_b32 s79, 0x1493000
	s_mov_b32 s80, 0x1496000
	s_mov_b32 s81, 0x1498000
	s_mov_b32 s82, 0x149b000
	s_mov_b32 s83, 0x149d000
	s_mov_b32 s41, 0
	s_branch .Lcx4_681

; __device__ __forceinline__ unsigned pk2(float lo, float hi) { return f2bf(lo) | (f2bf(hi) << 16); }
; __device__ __forceinline__ void transpose_item(const float* __restrict__ W, int K, int N, bf16* __restrict__ WT, const float* __restrict__ ksc, int mode, int row_off, int item, int lane) {
;     const int nblk = N / 64, kb = item / nblk, nb = item % nblk, k0 = 64 * kb, n = 64 * nb + lane;
;     const float* src = W + (size_t)k0 * N + n;
;     float v[64];
; #pragma unroll
;     for (int i = 0; i < 64; ++i) v[i] = __builtin_nontemporal_load(src + (size_t)i * N);
;     if (ksc) {
; #pragma unroll
;         for (int i = 0; i < 64; ++i) v[i] *= ksc[k0 + i];
;     }
;     bf16* dst = WT + (size_t)(row_off + map_row(n, mode)) * K + k0;
; #pragma unroll
;     for (int j = 0; j < 8; ++j) { v4u o; o.x = pk2(v[8 * j], v[8 * j + 1]); o.y = pk2(v[8 * j + 2], v[8 * j + 3]); o.z = pk2(v[8 * j + 4], v[8 * j + 5]); o.w = pk2(v[8 * j + 6], v[8 * j + 7]);
;         *(v4u*)(dst + 8 * j) = o; }
; __device__ __forceinline__ void convert_layer(ArgsP a, int L, int first, int stride, int lane) {
;     ...
;     for (int r = first; r < I_L; r += stride) {
;         if (r < I_IN) transpose_item(a->in[3] + (size_t)L * D * INW, D, INW, WIN + (size_t)L * INW * D, a->in[2] + L * D, 1, 0, r, lane);
;         else if (r < I_IN + I_OUT) transpose_item(a->in[4] + (size_t)L * D * D, D, D, WOUT + (size_t)L * D * D, nullptr, 0, 0, r - I_IN, lane);
;         else if (r < I_IN + I_OUT + I_GU) transpose_item(a->in[18] + (size_t)L * D * GU, D, GU, WGU + (size_t)L * GU * D, a->in[17] + L * D, 2, 0, r - I_IN - I_OUT, lane);
;         else transpose_item(a->in[19] + (size_t)L * FFN * D, FFN, D, WDN + (size_t)L * D * FFN, nullptr, 0, 0, r - I_IN - I_OUT - I_GU, lane);
;     }
.Lcx4_680:
	s_add_i32 s14, s1, 0x400
	s_add_i32 s4, s4, 0x8000
	s_add_i32 s5, s5, 0x1000
	s_add_i32 s3, s3, 0x10000
	v_add_u32_e32 v82, 0x10000, v82
	s_cmpk_lt_i32 s1, 0x0
	s_mov_b32 s1, s14
	global_store_dwordx4 v[78:79], v[0:3], off offset:112
	s_cbranch_scc0 .Lcx4_700

; __device__ __forceinline__ ArgsP args_ptr() { ArgsP p = (ArgsP)__builtin_amdgcn_kernarg_segment_ptr(); asm volatile("" : "+s"(p)); return p; }
; #define TIDS() int lane_ = (int)__builtin_amdgcn_mbcnt_hi(~0u, __builtin_amdgcn_mbcnt_lo(~0u, 0u)); asm volatile("" : "+v"(lane_)); const int lane = lane_ & 63, wave = wave_s & 7, tid = wave * 64 + lane; const int G = gridDim.x, bx = blockIdx.x; (void)lane; (void)wave; (void)tid; (void)G; (void)bx
; __device__ __forceinline__ void phase_A(unsigned char* lds, int wave_s, int L) {
;     ArgsP a = args_ptr(); TIDS(); unsigned char* ws = a->ws; const int j = L >> 1;
;     pg8::Gemm g{(bf16*)(ws + WS_XB), (bf16*)(ws + WS_WIN) + (size_t)L * INW * D, M, INW, D}; pg8::StaticOrder S; S.init(M, INW, G, bx);
;     pg8::EpiU E{(bf16*)(ws + WS_U), (const float*)(ws + WS_SS), L & 1, a->in[10] + j * 64, a->in[11] + j * 64, a->in[7] + L * 64, 0.125f * 1.4426950408889634f};
;     if (L + 1 < DEPTH && bx >= 128 && bx < 224) { convert_layer(args_ptr(), L + 1, (bx - 128) * NWAVES + wave, 96 * NWAVES, lane); asm volatile("s_waitcnt vmcnt(0)" ::: "memory"); }
;     pg8::gemm_phase<pg8::EpiU, pg8::StaticOrder, true, true>((pg8::PG8_LAS_T*)lds, g, S, E, tid);
.Lcx4_700:
	s_waitcnt vmcnt(0)
	v_mov_b32_e32 v1, v128
	v_mov_b32_e32 v2, v129
	v_mov_b32_e32 v3, v130
	v_mov_b32_e32 v64, v131
	v_mov_b32_e32 v65, v132
	v_mov_b32_e32 v66, v133
	v_mov_b32_e32 v67, v134
	v_mov_b32_e32 v68, v135
	v_mov_b32_e32 v69, v136
	v_mov_b32_e32 v70, v137
	v_mov_b32_e32 v71, v138
	v_mov_b32_e32 v72, v139
	v_mov_b32_e32 v73, v140
	v_mov_b32_e32 v74, v141
	v_mov_b32_e32 v75, v142
	v_mov_b32_e32 v76, v143
	v_mov_b32_e32 v77, v144
	v_mov_b32_e32 v78, v145
	v_mov_b32_e32 v79, v146
	v_mov_b32_e32 v81, v147
	v_mov_b32_e32 v82, v148
	v_mov_b32_e32 v83, v149
	v_mov_b32_e32 v84, v150
	v_mov_b32_e32 v85, v151
	v_mov_b32_e32 v86, v152
	v_mov_b32_e32 v87, v153
	v_mov_b32_e32 v88, v154
	v_mov_b32_e32 v89, v155
	v_mov_b32_e32 v90, v156
	v_mov_b32_e32 v91, v157
	v_readlane_b32 s1, v253, 0
	v_readlane_b32 s30, v253, 1
	v_readlane_b32 s31, v253, 2
	v_readlane_b32 s34, v253, 3
	v_readlane_b32 s35, v253, 4
	v_readlane_b32 s36, v253, 5
	v_readlane_b32 s37, v253, 6
	v_readlane_b32 s38, v253, 7
	v_readlane_b32 s39, v253, 8
	v_readlane_b32 s41, v253, 9
	v_readlane_b32 s44, v253, 10
	v_readlane_b32 s45, v253, 11
	v_readlane_b32 s46, v253, 12
	v_readlane_b32 s47, v253, 13
	v_readlane_b32 s48, v253, 14
	v_readlane_b32 s49, v253, 15
	v_readlane_b32 s50, v253, 16
	v_readlane_b32 s52, v253, 17
	v_readlane_b32 s63, v253, 18
	v_readlane_b32 s64, v253, 19
	v_readlane_b32 s65, v253, 20
	v_readlane_b32 s74, v253, 21
	v_readlane_b32 s75, v253, 22
	v_readlane_b32 s77, v253, 23
	v_readlane_b32 s82, v253, 24
	v_readlane_b32 s83, v253, 25
	v_readlane_b32 s84, v253, 26
	v_readlane_b32 s85, v253, 27
	s_nop 4
.Lcx4_skip:
	v_mov_b32_e32 v0, v201
	s_load_dwordx2 s[26:27], s[12:13], 0xa8
	s_load_dwordx2 s[24:25], s[12:13], 0x38
	v_readlane_b32 s4, v252, 12
	v_readlane_b32 s5, v252, 13
	s_and_b64 vcc, exec, s[4:5]
	v_and_b32_e32 v80, 63, v0
	s_cbranch_vccnz .LBB0_1177
	v_readlane_b32 s14, v252, 15
	v_readlane_b32 s15, v252, 16
	s_load_dwordx2 s[12:13], s[14:15], 0xa8
	v_readlane_b32 s0, v252, 1
	v_readlane_b32 s3, v252, 2
	s_add_i32 s0, s3, s0
	s_add_i32 s3, s0, 0xfffffc00
	s_waitcnt lgkmcnt(0)
	s_add_u32 s20, s12, 0x5980000
	s_addc_u32 s21, s13, 0
	s_add_u32 s22, s12, 0x3e00000
	s_addc_u32 s23, s13, 0
	s_add_u32 s42, s12, 0x1b00000
	s_addc_u32 s43, s13, 0
	s_add_u32 s44, s12, 0x1000000
	v_lshlrev_b32_e32 v0, 2, v80
	s_addc_u32 s45, s13, 0
	s_lshl_b32 s12, s3, 6
	v_and_b32_e32 v81, 0x80, v0
	v_or_b32_e32 v82, s12, v80
	s_lshl_b32 s13, s3, 5
	s_lshl_b32 s40, s3, 2
	v_mov_b32_e32 v13, 0
	s_movk_i32 s48, 0x7fff
	s_mov_b32 s49, 0xffff0000
	v_mov_b32_e32 v83, 0x3000
	v_mov_b32_e32 v84, 1
	s_mov_b32 s50, 0x1e9b000
	s_mov_b32 s51, 0x1e9d000
	s_mov_b32 s47, 0
	s_branch .LBB0_1157

; __device__ __forceinline__ ArgsP args_ptr() { ArgsP p = (ArgsP)__builtin_amdgcn_kernarg_segment_ptr(); asm volatile("" : "+s"(p)); return p; }
; __device__ __forceinline__ void convert_layer(ArgsP a, int L, int first, int stride, int lane) {
;     ...
;     for (int r = first; r < I_L; r += stride) {
;         if (r < I_IN) transpose_item(a->in[3] + (size_t)L * D * INW, D, INW, WIN + (size_t)L * INW * D, a->in[2] + L * D, 1, 0, r, lane);
;         else if (r < I_IN + I_OUT) transpose_item(a->in[4] + (size_t)L * D * D, D, D, WOUT + (size_t)L * D * D, nullptr, 0, 0, r - I_IN, lane);
;         else if (r < I_IN + I_OUT + I_GU) transpose_item(a->in[18] + (size_t)L * D * GU, D, GU, WGU + (size_t)L * GU * D, a->in[17] + L * D, 2, 0, r - I_IN - I_OUT, lane);
;         else transpose_item(a->in[19] + (size_t)L * FFN * D, FFN, D, WDN + (size_t)L * D * FFN, nullptr, 0, 0, r - I_IN - I_OUT - I_GU, lane);
;     }
; __device__ __forceinline__ void phase_A(unsigned char* lds, int wave_s, int L) {
;     ...
;     if (L + 1 < DEPTH && bx >= 128 && bx < 224) { convert_layer(args_ptr(), L + 1, (bx - 128) * NWAVES + wave, 96 * NWAVES, lane); asm volatile("s_waitcnt vmcnt(0)" ::: "memory"); }
.LBB0_1156:
	s_add_i32 s0, s3, 0x300
	s_addk_i32 s13, 0x6000
	s_addk_i32 s40, 0xc00
	s_add_i32 s12, s12, 0xc000
	v_add_u32_e32 v82, 0xc000, v82
	s_cmpk_lt_i32 s3, 0
	s_mov_b32 s3, s0
	global_store_dwordx4 v[78:79], v[0:3], off offset:112
	s_cbranch_scc0 .LBB0_1176

; __device__ __forceinline__ ArgsP args_ptr() { ArgsP p = (ArgsP)__builtin_amdgcn_kernarg_segment_ptr(); asm volatile("" : "+s"(p)); return p; }
; #define TIDS() int lane_ = (int)__builtin_amdgcn_mbcnt_hi(~0u, __builtin_amdgcn_mbcnt_lo(~0u, 0u)); asm volatile("" : "+v"(lane_)); const int lane = lane_ & 63, wave = wave_s & 7, tid = wave * 64 + lane; const int G = gridDim.x, bx = blockIdx.x; (void)lane; (void)wave; (void)tid; (void)G; (void)bx
; __device__ __forceinline__ void convert_layer(ArgsP a, int L, int first, int stride, int lane) {
;     unsigned char* ws = a->ws;
;     bf16* WIN = (bf16*)(ws + WS_WIN); bf16* WOUT = (bf16*)(ws + WS_WOUT); bf16* WGU = (bf16*)(ws + WS_WGU); bf16* WDN = (bf16*)(ws + WS_WDN);
;     for (int r = first; r < I_L; r += stride) {
;         if (r < I_IN) transpose_item(a->in[3] + (size_t)L * D * INW, D, INW, WIN + (size_t)L * INW * D, a->in[2] + L * D, 1, 0, r, lane);
;         else if (r < I_IN + I_OUT) transpose_item(a->in[4] + (size_t)L * D * D, D, D, WOUT + (size_t)L * D * D, nullptr, 0, 0, r - I_IN, lane);
;         else if (r < I_IN + I_OUT + I_GU) transpose_item(a->in[18] + (size_t)L * D * GU, D, GU, WGU + (size_t)L * GU * D, a->in[17] + L * D, 2, 0, r - I_IN - I_OUT, lane);
;         else transpose_item(a->in[19] + (size_t)L * FFN * D, FFN, D, WDN + (size_t)L * D * FFN, nullptr, 0, 0, r - I_IN - I_OUT - I_GU, lane);
;     }
; }
; __device__ __forceinline__ void phase_D(unsigned char* lds, int wave_s, int L) {
;     ArgsP a = args_ptr(); TIDS(); unsigned char* ws = a->ws;
;     pg8::Gemm g{(bf16*)(ws + WS_XB), (bf16*)(ws + WS_WGU) + (size_t)L * GU * D, M, GU, D}; pg8::StaticOrder S; S.init(M, GU, G, bx);
;     pg8::EpiSwi E{(bf16*)(ws + WS_ACT), (const float*)(ws + WS_SS)};
;     pg8::gemm_phase<pg8::EpiSwi, pg8::StaticOrder, true, true>((pg8::PG8_LAS_T*)lds, g, S, E, tid);
.LBB0_1579:
	s_or_b64 exec, exec, s[8:9]
	v_readlane_b32 s8, v252, 15
	v_readlane_b32 s9, v252, 16
	s_waitcnt lgkmcnt(0)
	v_mov_b32_e32 v0, v201
	v_readlane_b32 s0, v252, 5
	v_readlane_b32 s4, v252, 33
	s_barrier
	s_cmp_lt_u32 s2, 0x80
	s_cbranch_scc1 .Lcx5_skip
	s_cmp_ge_u32 s2, 0x100
	s_cbranch_scc1 .Lcx5_skip
	v_mov_b32_e32 v128, v0
	v_mov_b32_e32 v129, v2
	v_mov_b32_e32 v130, v3
	v_mov_b32_e32 v131, v64
	v_mov_b32_e32 v132, v65
	v_mov_b32_e32 v133, v66
	v_mov_b32_e32 v134, v67
	v_mov_b32_e32 v135, v68
	v_mov_b32_e32 v136, v69
	v_mov_b32_e32 v137, v70
	v_mov_b32_e32 v138, v71
	v_mov_b32_e32 v139, v72
	v_mov_b32_e32 v140, v73
	v_mov_b32_e32 v141, v74
	v_mov_b32_e32 v142, v75
	v_mov_b32_e32 v143, v76
	v_mov_b32_e32 v144, v77
	v_mov_b32_e32 v145, v78
	v_mov_b32_e32 v146, v79
	v_mov_b32_e32 v147, v80
	v_mov_b32_e32 v148, v81
	v_mov_b32_e32 v149, v82
	v_mov_b32_e32 v150, v83
	v_mov_b32_e32 v151, v84
	v_mov_b32_e32 v152, v85
	v_mov_b32_e32 v153, v86
	v_mov_b32_e32 v154, v87
	v_mov_b32_e32 v155, v88
	v_mov_b32_e32 v156, v89
	v_mov_b32_e32 v157, v90
	v_mov_b32_e32 v158, v91
	v_writelane_b32 v253, s0, 0
	v_writelane_b32 v253, s4, 1
	v_writelane_b32 v253, s18, 2
	v_writelane_b32 v253, s42, 3
	v_writelane_b32 v253, s43, 4
	v_writelane_b32 v253, s44, 5
	v_writelane_b32 v253, s45, 6
	v_writelane_b32 v253, s46, 7
	v_writelane_b32 v253, s47, 8
	v_writelane_b32 v253, s50, 9
	v_and_b32_e32 v80, 63, v201
	v_readlane_b32 s14, v252, 15
	v_readlane_b32 s15, v252, 16
	s_load_dwordx2 s[12:13], s[14:15], 0xa8
	v_readlane_b32 s0, v252, 1
	v_readlane_b32 s3, v252, 2
	s_add_i32 s0, s3, s0
	s_add_i32 s3, s0, 0xffffff00
	s_waitcnt lgkmcnt(0)
	s_add_u32 s20, s12, 0x5980000
	s_addc_u32 s21, s13, 0
	s_add_u32 s22, s12, 0x3e00000
	s_addc_u32 s23, s13, 0
	s_add_u32 s42, s12, 0x1b00000
	s_addc_u32 s43, s13, 0
	s_add_u32 s44, s12, 0x1000000
	v_lshlrev_b32_e32 v0, 2, v80
	s_addc_u32 s45, s13, 0
	s_lshl_b32 s12, s3, 6
	v_and_b32_e32 v81, 0x80, v0
	v_or_b32_e32 v82, s12, v80
	s_lshl_b32 s13, s3, 5
	s_lshl_b32 s40, s3, 2
	v_mov_b32_e32 v13, 0
	s_movk_i32 s48, 0x7fff
	s_mov_b32 s49, 0xffff0000
	v_mov_b32_e32 v83, 0x3000
	v_mov_b32_e32 v84, 1
	s_mov_b32 s50, 0x1e9b000
	s_mov_b32 s51, 0x1e9d000
	s_mov_b32 s47, 0
	s_branch .Lcx5_1157

; __device__ __forceinline__ unsigned pk2(float lo, float hi) { return f2bf(lo) | (f2bf(hi) << 16); }
; __device__ __forceinline__ void transpose_item(const float* __restrict__ W, int K, int N, bf16* __restrict__ WT, const float* __restrict__ ksc, int mode, int row_off, int item, int lane) {
;     const int nblk = N / 64, kb = item / nblk, nb = item % nblk, k0 = 64 * kb, n = 64 * nb + lane;
;     const float* src = W + (size_t)k0 * N + n;
;     float v[64];
; #pragma unroll
;     for (int i = 0; i < 64; ++i) v[i] = __builtin_nontemporal_load(src + (size_t)i * N);
;     if (ksc) {
; #pragma unroll
;         for (int i = 0; i < 64; ++i) v[i] *= ksc[k0 + i];
;     }
;     bf16* dst = WT + (size_t)(row_off + map_row(n, mode)) * K + k0;
; #pragma unroll
;     for (int j = 0; j < 8; ++j) { v4u o; o.x = pk2(v[8 * j], v[8 * j + 1]); o.y = pk2(v[8 * j + 2], v[8 * j + 3]); o.z = pk2(v[8 * j + 4], v[8 * j + 5]); o.w = pk2(v[8 * j + 6], v[8 * j + 7]);
;         *(v4u*)(dst + 8 * j) = o; }
; __device__ __forceinline__ void convert_layer(ArgsP a, int L, int first, int stride, int lane) {
;     ...
;     for (int r = first; r < I_L; r += stride) {
;         if (r < I_IN) transpose_item(a->in[3] + (size_t)L * D * INW, D, INW, WIN + (size_t)L * INW * D, a->in[2] + L * D, 1, 0, r, lane);
;         else if (r < I_IN + I_OUT) transpose_item(a->in[4] + (size_t)L * D * D, D, D, WOUT + (size_t)L * D * D, nullptr, 0, 0, r - I_IN, lane);
;         else if (r < I_IN + I_OUT + I_GU) transpose_item(a->in[18] + (size_t)L * D * GU, D, GU, WGU + (size_t)L * GU * D, a->in[17] + L * D, 2, 0, r - I_IN - I_OUT, lane);
;         else transpose_item(a->in[19] + (size_t)L * FFN * D, FFN, D, WDN + (size_t)L * D * FFN, nullptr, 0, 0, r - I_IN - I_OUT - I_GU, lane);
;     }
.Lcx5_1156:
	s_add_i32 s0, s3, 0x400
	s_add_i32 s13, s13, 0x8000
	s_add_i32 s40, s40, 0x1000
	s_add_i32 s12, s12, 0x10000
	v_add_u32_e32 v82, 0x10000, v82
	s_cmpk_lt_i32 s3, 0x700
	s_mov_b32 s3, s0
	global_store_dwordx4 v[78:79], v[0:3], off offset:112
	s_cbranch_scc0 .Lcx5_1176

; __device__ __forceinline__ ArgsP args_ptr() { ArgsP p = (ArgsP)__builtin_amdgcn_kernarg_segment_ptr(); asm volatile("" : "+s"(p)); return p; }
; #define TIDS() int lane_ = (int)__builtin_amdgcn_mbcnt_hi(~0u, __builtin_amdgcn_mbcnt_lo(~0u, 0u)); asm volatile("" : "+v"(lane_)); const int lane = lane_ & 63, wave = wave_s & 7, tid = wave * 64 + lane; const int G = gridDim.x, bx = blockIdx.x; (void)lane; (void)wave; (void)tid; (void)G; (void)bx
; __device__ __forceinline__ void convert_layer(ArgsP a, int L, int first, int stride, int lane) {
;     unsigned char* ws = a->ws;
;     bf16* WIN = (bf16*)(ws + WS_WIN); bf16* WOUT = (bf16*)(ws + WS_WOUT); bf16* WGU = (bf16*)(ws + WS_WGU); bf16* WDN = (bf16*)(ws + WS_WDN);
;     for (int r = first; r < I_L; r += stride) {
;         if (r < I_IN) transpose_item(a->in[3] + (size_t)L * D * INW, D, INW, WIN + (size_t)L * INW * D, a->in[2] + L * D, 1, 0, r, lane);
;         else if (r < I_IN + I_OUT) transpose_item(a->in[4] + (size_t)L * D * D, D, D, WOUT + (size_t)L * D * D, nullptr, 0, 0, r - I_IN, lane);
;         else if (r < I_IN + I_OUT + I_GU) transpose_item(a->in[18] + (size_t)L * D * GU, D, GU, WGU + (size_t)L * GU * D, a->in[17] + L * D, 2, 0, r - I_IN - I_OUT, lane);
;         else transpose_item(a->in[19] + (size_t)L * FFN * D, FFN, D, WDN + (size_t)L * D * FFN, nullptr, 0, 0, r - I_IN - I_OUT - I_GU, lane);
;     }
; }
; __device__ __forceinline__ void phase_A(unsigned char* lds, int wave_s, int L) {
;     ArgsP a = args_ptr(); TIDS(); unsigned char* ws = a->ws; const int j = L >> 1;
;     pg8::Gemm g{(bf16*)(ws + WS_XB), (bf16*)(ws + WS_WIN) + (size_t)L * INW * D, M, INW, D}; pg8::StaticOrder S; S.init(M, INW, G, bx);
;     pg8::EpiU E{(bf16*)(ws + WS_U), (const float*)(ws + WS_SS), L & 1, a->in[10] + j * 64, a->in[11] + j * 64, a->in[7] + L * 64, 0.125f * 1.4426950408889634f};
;     if (L + 1 < DEPTH && bx >= 128 && bx < 224) { convert_layer(args_ptr(), L + 1, (bx - 128) * NWAVES + wave, 96 * NWAVES, lane); asm volatile("s_waitcnt vmcnt(0)" ::: "memory"); }
;     pg8::gemm_phase<pg8::EpiU, pg8::StaticOrder, true, true>((pg8::PG8_LAS_T*)lds, g, S, E, tid);
.LBB0_1745:
	s_or_b64 exec, exec, s[8:9]
	v_readlane_b32 s14, v252, 15
	v_readlane_b32 s15, v252, 16
	s_waitcnt lgkmcnt(0)
	v_mov_b32_e32 v0, v201
	v_readlane_b32 s0, v252, 6
	v_readlane_b32 s4, v252, 7
	s_barrier
	s_cmp_lt_u32 s2, 0xe0
	s_cbranch_scc1 .Lcx6_skip
	s_cmp_ge_u32 s2, 0xf8
	s_cbranch_scc1 .Lcx6_skip
	v_mov_b32_e32 v128, v0
	v_mov_b32_e32 v129, v2
	v_mov_b32_e32 v130, v3
	v_mov_b32_e32 v131, v64
	v_mov_b32_e32 v132, v65
	v_mov_b32_e32 v133, v66
	v_mov_b32_e32 v134, v67
	v_mov_b32_e32 v135, v68
	v_mov_b32_e32 v136, v69
	v_mov_b32_e32 v137, v70
	v_mov_b32_e32 v138, v71
	v_mov_b32_e32 v139, v72
	v_mov_b32_e32 v140, v73
	v_mov_b32_e32 v141, v74
	v_mov_b32_e32 v142, v75
	v_mov_b32_e32 v143, v76
	v_mov_b32_e32 v144, v77
	v_mov_b32_e32 v145, v78
	v_mov_b32_e32 v146, v79
	v_mov_b32_e32 v147, v80
	v_mov_b32_e32 v148, v81
	v_mov_b32_e32 v149, v82
	v_mov_b32_e32 v150, v83
	v_mov_b32_e32 v151, v84
	v_mov_b32_e32 v152, v85
	v_mov_b32_e32 v153, v86
	v_mov_b32_e32 v154, v87
	v_mov_b32_e32 v155, v88
	v_mov_b32_e32 v156, v89
	v_mov_b32_e32 v157, v90
	v_mov_b32_e32 v158, v91
	v_writelane_b32 v253, s0, 0
	v_writelane_b32 v253, s4, 1
	v_writelane_b32 v253, s14, 2
	v_writelane_b32 v253, s15, 3
	v_writelane_b32 v253, s44, 4
	v_writelane_b32 v253, s45, 5
	v_and_b32_e32 v80, 63, v201
	v_readlane_b32 s14, v252, 15
	v_readlane_b32 s15, v252, 16
	s_load_dwordx2 s[12:13], s[14:15], 0xa8
	v_readlane_b32 s0, v252, 1
	v_readlane_b32 s3, v252, 2
	s_add_i32 s0, s3, s0
	s_add_i32 s3, s0, 0x400
	s_waitcnt lgkmcnt(0)
	s_add_u32 s20, s12, 0x5980000
	s_addc_u32 s21, s13, 0
	s_add_u32 s22, s12, 0x3e00000
	s_addc_u32 s23, s13, 0
	s_add_u32 s42, s12, 0x1b00000
	s_addc_u32 s43, s13, 0
	s_add_u32 s44, s12, 0x1000000
	v_lshlrev_b32_e32 v0, 2, v80
	s_addc_u32 s45, s13, 0
	s_lshl_b32 s12, s3, 6
	v_and_b32_e32 v81, 0x80, v0
	v_or_b32_e32 v82, s12, v80
	s_lshl_b32 s13, s3, 5
	s_lshl_b32 s40, s3, 2
	v_mov_b32_e32 v13, 0
	s_movk_i32 s48, 0x7fff
	s_mov_b32 s49, 0xffff0000
	v_mov_b32_e32 v83, 0x3000
	v_mov_b32_e32 v84, 1
	s_mov_b32 s50, 0x1e9b000
	s_mov_b32 s51, 0x1e9d000
	s_mov_b32 s47, 0
	s_branch .Lcx6_1157

; __device__ __forceinline__ unsigned pk2(float lo, float hi) { return f2bf(lo) | (f2bf(hi) << 16); }
; __device__ __forceinline__ void transpose_item(const float* __restrict__ W, int K, int N, bf16* __restrict__ WT, const float* __restrict__ ksc, int mode, int row_off, int item, int lane) {
;     const int nblk = N / 64, kb = item / nblk, nb = item % nblk, k0 = 64 * kb, n = 64 * nb + lane;
;     const float* src = W + (size_t)k0 * N + n;
;     float v[64];
; #pragma unroll
;     for (int i = 0; i < 64; ++i) v[i] = __builtin_nontemporal_load(src + (size_t)i * N);
;     if (ksc) {
; #pragma unroll
;         for (int i = 0; i < 64; ++i) v[i] *= ksc[k0 + i];
;     }
;     bf16* dst = WT + (size_t)(row_off + map_row(n, mode)) * K + k0;
; #pragma unroll
;     for (int j = 0; j < 8; ++j) { v4u o; o.x = pk2(v[8 * j], v[8 * j + 1]); o.y = pk2(v[8 * j + 2], v[8 * j + 3]); o.z = pk2(v[8 * j + 4], v[8 * j + 5]); o.w = pk2(v[8 * j + 6], v[8 * j + 7]);
;         *(v4u*)(dst + 8 * j) = o; }
; __device__ __forceinline__ void convert_layer(ArgsP a, int L, int first, int stride, int lane) {
;     ...
;     for (int r = first; r < I_L; r += stride) {
;         if (r < I_IN) transpose_item(a->in[3] + (size_t)L * D * INW, D, INW, WIN + (size_t)L * INW * D, a->in[2] + L * D, 1, 0, r, lane);
;         else if (r < I_IN + I_OUT) transpose_item(a->in[4] + (size_t)L * D * D, D, D, WOUT + (size_t)L * D * D, nullptr, 0, 0, r - I_IN, lane);
;         else if (r < I_IN + I_OUT + I_GU) transpose_item(a->in[18] + (size_t)L * D * GU, D, GU, WGU + (size_t)L * GU * D, a->in[17] + L * D, 2, 0, r - I_IN - I_OUT, lane);
;         else transpose_item(a->in[19] + (size_t)L * FFN * D, FFN, D, WDN + (size_t)L * D * FFN, nullptr, 0, 0, r - I_IN - I_OUT - I_GU, lane);
;     }
.Lcx6_1156:
	s_add_i32 s0, s3, 0x400
	s_add_i32 s13, s13, 0x8000
	s_add_i32 s40, s40, 0x1000
	s_add_i32 s12, s12, 0x10000
	v_add_u32_e32 v82, 0x10000, v82
	s_cmpk_lt_i32 s3, 0x0
	s_mov_b32 s3, s0
	global_store_dwordx4 v[78:79], v[0:3], off offset:112
	s_cbranch_scc0 .Lcx6_1176

;     __device__ bool next(int i, Unit& u) const { if (i > 0) return false; const int t = c - first; if (t < 0 || t >= nM * nN) return false; u.pm = t % nM; u.pn = t / nM; return true; }
; __device__ __forceinline__ ArgsP args_ptr() { ArgsP p = (ArgsP)__builtin_amdgcn_kernarg_segment_ptr(); asm volatile("" : "+s"(p)); return p; }
; #define TIDS() int lane_ = (int)__builtin_amdgcn_mbcnt_hi(~0u, __builtin_amdgcn_mbcnt_lo(~0u, 0u)); asm volatile("" : "+v"(lane_)); const int lane = lane_ & 63, wave = wave_s & 7, tid = wave * 64 + lane; const int G = gridDim.x, bx = blockIdx.x; (void)lane; (void)wave; (void)tid; (void)G; (void)bx
;     __host__ __device__ bool next(int i, Unit& u) const {
;         const long L = (long)i * G + c; if (L >= nwg) return false;
;         int wgid = (int)L; { const int q = nwg / NXCD, r = nwg % NXCD, xcd = wgid % NXCD, off = wgid / NXCD; wgid = (xcd < r ? xcd * (q + 1) : r * (q + 1) + (xcd - r) * q) + off; }
;         const int nig = WGM * nN, gid = wgid / nig, fm = gid * WGM, gsz = (nM - fm) < WGM ? (nM - fm) : WGM;
;         u.pm = fm + ((wgid % nig) % gsz); u.pn = (wgid % nig) / gsz; return true;
; __device__ __forceinline__ void phase_A(unsigned char* lds, int wave_s, int L) {
;     ArgsP a = args_ptr(); TIDS(); unsigned char* ws = a->ws; const int j = L >> 1;
;     pg8::Gemm g{(bf16*)(ws + WS_XB), (bf16*)(ws + WS_WIN) + (size_t)L * INW * D, M, INW, D}; pg8::StaticOrder S; S.init(M, INW, G, bx);
;     pg8::EpiU E{(bf16*)(ws + WS_U), (const float*)(ws + WS_SS), L & 1, a->in[10] + j * 64, a->in[11] + j * 64, a->in[7] + L * 64, 0.125f * 1.4426950408889634f};
;     if (L + 1 < DEPTH && bx >= 128 && bx < 224) { convert_layer(args_ptr(), L + 1, (bx - 128) * NWAVES + wave, 96 * NWAVES, lane); asm volatile("s_waitcnt vmcnt(0)" ::: "memory"); }
;     pg8::gemm_phase<pg8::EpiU, pg8::StaticOrder, true, true>((pg8::PG8_LAS_T*)lds, g, S, E, tid);
.Lcx6_1176:
	s_waitcnt vmcnt(0)
	v_mov_b32_e32 v0, v128
	v_mov_b32_e32 v2, v129
	v_mov_b32_e32 v3, v130
	v_mov_b32_e32 v64, v131
	v_mov_b32_e32 v65, v132
	v_mov_b32_e32 v66, v133
	v_mov_b32_e32 v67, v134
	v_mov_b32_e32 v68, v135
	v_mov_b32_e32 v69, v136
	v_mov_b32_e32 v70, v137
	v_mov_b32_e32 v71, v138
	v_mov_b32_e32 v72, v139
	v_mov_b32_e32 v73, v140
	v_mov_b32_e32 v74, v141
	v_mov_b32_e32 v75, v142
	v_mov_b32_e32 v76, v143
	v_mov_b32_e32 v77, v144
	v_mov_b32_e32 v78, v145
	v_mov_b32_e32 v79, v146
	v_mov_b32_e32 v80, v147
	v_mov_b32_e32 v81, v148
	v_mov_b32_e32 v82, v149
	v_mov_b32_e32 v83, v150
	v_mov_b32_e32 v84, v151
	v_mov_b32_e32 v85, v152
	v_mov_b32_e32 v86, v153
	v_mov_b32_e32 v87, v154
	v_mov_b32_e32 v88, v155
	v_mov_b32_e32 v89, v156
	v_mov_b32_e32 v90, v157
	v_mov_b32_e32 v91, v158
	v_readlane_b32 s0, v253, 0
	v_readlane_b32 s4, v253, 1
	v_readlane_b32 s14, v253, 2
	v_readlane_b32 s15, v253, 3
	v_readlane_b32 s44, v253, 4
	v_readlane_b32 s45, v253, 5
	s_nop 4
.Lcx6_skip:
	v_readlane_b32 s5, v252, 8
	v_and_or_b32 v8, v0, 63, s0
	s_and_b64 vcc, exec, s[4:5]
	v_readfirstlane_b32 s24, v8
	s_cbranch_vccnz .LBB0_1747
	s_ashr_i32 s0, s2, 31
	s_lshr_b32 s0, s0, 29
	s_add_i32 s0, s2, s0
	s_ashr_i32 s3, s0, 3
	s_and_b32 s0, s0, -8
	s_sub_i32 s0, s2, s0
	s_cmp_lt_i32 s0, 0
	s_movk_i32 s4, 0x51
	s_cselect_b32 s4, s4, 0x50
	s_mul_i32 s0, s4, s0
	s_add_i32 s0, s0, s3
	s_mul_hi_i32 s3, s0, 0x66666667
	s_lshr_b32 s4, s3, 31
	s_ashr_i32 s3, s3, 5
	s_add_i32 s3, s3, s4
	s_lshl_b32 s4, s3, 3
	s_mulk_i32 s3, 0x50
	s_sub_i32 s0, s0, s3
	s_bfe_i32 s3, s0, 0x80000
	s_bfe_u32 s3, s3, 0x3000c
	s_add_i32 s3, s0, s3
	s_bfe_i32 s5, s3, 0x80000
	s_and_b32 s3, s3, 0xf8
	s_sub_i32 s0, s0, s3
	s_sext_i32_i16 s5, s5
	s_sext_i32_i8 s0, s0
	s_add_i32 s44, s4, s0
	s_ashr_i32 s8, s5, 3
